# co-resident block of each prompt-scan block starts queue work only after the scan passed chunk 176 of 512
# speedup vs baseline: 1.0021x; 1.0021x over previous
; DI void scan_task(const Params& p, int l, int isP, int b, int h, int rg, char* smem, const bool dry) {
;     ...
;     {
;       const float yl = rowsum16(yprev);
;       ykeep1 = (jq == 15) ? yl : ykeep1;
;     }
;     if (!dry) { yo[0] = ykeep0; yo[(size_t)16 * 512] = ykeep1; }
;     if (more) sstore((c + 1) & 1);
;     __syncthreads();
;   }
;   float* so = isP ? p.out + O_WKVP + ((size_t)((l * 2 + b) * 8 + h) * 64 + i) * 64 + jq * 4
;                   : p.out + O_WKVS + ((size_t)((l * 32 + b) * 8 + h) * 64 + i) * 64 + jq * 4;
;   if (!dry) *(float4*)so = make_float4(Sa.x, Sa.y, Sb.x, Sb.y);
;   __builtin_amdgcn_s_setprio(0);
.Lscan_tailB:
	v_add_f32_dpp v75, v66, v66 row_mirror row_mask:0xf bank_mask:0x3
	v_add_f32_dpp v74, v74, v74 row_half_mirror row_mask:0xf bank_mask:0x5
	v_add_f32_dpp v68, v68, v68 quad_perm:[1,0,3,2] row_mask:0xf bank_mask:0xf
	v_add_f32_dpp v75, v67, v67 row_mirror row_mask:0xf bank_mask:0xc
	v_add_f32_dpp v70, v70, v70 quad_perm:[1,0,3,2] row_mask:0xf bank_mask:0xf
	v_add_f32_dpp v72, v72, v72 quad_perm:[1,0,3,2] row_mask:0xf bank_mask:0xf
	v_add_f32_dpp v74, v75, v75 row_half_mirror row_mask:0xf bank_mask:0xa
	v_add_f32_dpp v68, v68, v68 quad_perm:[2,3,0,1] row_mask:0xf bank_mask:0xf
	v_add_f32_dpp v70, v70, v70 quad_perm:[2,3,0,1] row_mask:0xf bank_mask:0xf
	v_add_f32_dpp v74, v74, v74 quad_perm:[1,0,3,2] row_mask:0xf bank_mask:0xf
	v_add_f32_dpp v72, v72, v72 quad_perm:[2,3,0,1] row_mask:0xf bank_mask:0xf
	v_cndmask_b32_e64 v68, v68, v70, s[18:19]
	v_add_f32_dpp v74, v74, v74 quad_perm:[2,3,0,1] row_mask:0xf bank_mask:0xf
	v_cndmask_b32_e64 v72, v72, v74, s[18:19]
	v_cndmask_b32_e64 v68, v68, v72, s[20:21]
	global_store_dword v83, v68, s[14:15]
	s_add_u32 s14, s14, 0x8000
	s_addc_u32 s15, s15, 0
	s_cmp_eq_u32 s16, 176
	s_cbranch_scc0 .Lscan_nosig
	s_load_dwordx2 s[30:31], s[0:1], 0x1b0
	s_lshl_b32 s29, s93, 2
	s_addk_i32 s29, 0x3000
	v_mov_b32_e32 v252, s29
	v_mov_b32_e32 v253, 1
	v_cmp_eq_u32_e32 vcc, 0, v182
	s_and_saveexec_b64 s[34:35], vcc
	s_waitcnt lgkmcnt(0)
	global_atomic_add v252, v253, s[30:31]
	s_or_b64 exec, exec, s[34:35]
.Lscan_nosig:
	s_add_i32 s16, s16, 2
	s_cmp_lt_u32 s16, s17
	s_cbranch_scc1 .Lscan_loop
	s_waitcnt vmcnt(0)
	global_store_dwordx4 v59, v[4:7], s[24:25]
	v_readlane_b32 s10, v254, 51
	v_readlane_b32 s11, v254, 52
	s_setprio 0
	v_readlane_b32 s26, v254, 59
	v_readlane_b32 s27, v254, 60
